# v76 + XCD-local barriers in flag form (per-workgroup flag stores + 32-lane poll by the group's first workgroup + release word) instead of memory-side atomics
# speedup vs baseline: 1.0069x; 1.0069x over previous
.LBB0_233:
	s_mov_b64 s[6:7], s[0:1]
	s_getreg_b32 s8, hwreg(HW_REG_XCC_ID, 0, 4)
	s_waitcnt vmcnt(0)
	s_waitcnt vmcnt(0)
	v_add_u32_e32 v254, v254, v255
	v_cmp_ne_u32_e32 vcc, 17, v254
	s_nop 3
	s_cmp_eq_u64 vcc, 0
	s_cselect_b32 s99, 1, 0
	s_cmpk_lg_i32 s52, 0x100
	s_cselect_b32 s99, 0, s99
	s_barrier
	s_and_saveexec_b64 s[4:5], s[44:45]
	s_xor_b64 s[4:5], exec, s[4:5]
	s_cbranch_execz .LBB0_286
	s_cmp_eq_u32 s99, 0
	s_cbranch_scc1 .Lfb_skip_0
	s_load_dwordx2 s[8:9], s[0:1], 0x80
	s_and_b32 s10, s2, 7
	s_lshl_b32 s10, s10, 8
	s_add_i32 s10, s10, 0x1000
	s_lshr_b32 s11, s2, 3
	v_mov_b32_e32 v0, 1
	v_mov_b32_e32 v3, 0
	s_lshl_b32 s12, s11, 2
	v_mov_b32_e32 v1, s12
	s_mov_b32 s13, 0
	s_waitcnt lgkmcnt(0)
	s_add_u32 s8, s8, s10
	s_addc_u32 s9, s9, 0
	global_store_dword v1, v0, s[8:9]
	buffer_inv sc1
	s_cmp_eq_u32 s11, 0
	s_cbranch_scc1 .Lfb_lead_0
.Lfb_poll_0:
	global_load_dword v2, v3, s[8:9] offset:128 sc1
	s_waitcnt vmcnt(0)
	v_cmp_ge_u32_e32 vcc, v2, v0
	s_and_b64 vcc, exec, vcc
	s_cbranch_vccnz .Lfb_done_0
	s_sleep 1
	s_add_i32 s13, s13, 1
	s_cmp_lt_u32 s13, 0x1000
	s_cbranch_scc1 .Lfb_poll_0
	s_branch .Lfb_done_0
.Lfb_lead_0:
	s_mov_b64 s[16:17], exec
	s_mov_b64 exec, 0xffffffff
	v_mbcnt_lo_u32_b32 v4, -1, 0
	v_lshlrev_b32_e32 v4, 2, v4
	v_mov_b32_e32 v0, 1
.Lfb_lpoll_0:
	global_load_dword v5, v4, s[8:9] sc1
	s_waitcnt vmcnt(0)
	v_cmp_lt_u32_e32 vcc, v5, v0
	s_and_b64 vcc, exec, vcc
	s_cbranch_vccz .Lfb_lrel_0
	s_sleep 1
	s_add_i32 s13, s13, 1
	s_cmp_lt_u32 s13, 0x1000
	s_cbranch_scc1 .Lfb_lpoll_0
.Lfb_lrel_0:
	s_mov_b64 exec, s[16:17]
	global_store_dword v3, v0, s[8:9] offset:128

.Lfb_skip_0:
	s_add_i32 s9, 0, 0x23fe0
	v_mov_b32_e32 v0, s9
	s_load_dwordx2 s[6:7], s[6:7], 0x80
	s_waitcnt vmcnt(0) expcnt(0) lgkmcnt(0)
	ds_read_b32 v2, v0
	s_add_i32 s9, 0, 0x23fe4
	v_mov_b32_e32 v0, s9
	ds_read_b32 v0, v0
	s_and_b32 s33, s8, 15
	s_waitcnt lgkmcnt(1)
	v_cmp_ne_u32_e32 vcc, 0, v2
	s_cbranch_vccnz .LBB0_249
	s_load_dword s8, s[0:1], 0x90
	s_mov_b32 s59, 1
	v_mov_b32_e32 v16, 0
	s_waitcnt lgkmcnt(0)
	s_mul_i32 s58, s53, s8
	s_add_u32 s8, s6, 0x4200
	s_addc_u32 s9, s7, 0
	s_add_u32 s10, s6, 0x4400
	s_addc_u32 s11, s7, 0
	s_add_u32 s12, s6, 0x4500
	s_addc_u32 s13, s7, 0
	s_add_u32 s14, s6, 0x4600
	s_addc_u32 s15, s7, 0
	s_add_u32 s16, s6, 0x4700
	s_addc_u32 s17, s7, 0
	s_add_u32 s18, s6, 0x4800
	s_addc_u32 s19, s7, 0
	s_add_u32 s20, s6, 0x4900
	s_addc_u32 s21, s7, 0
	s_add_u32 s22, s6, 0x4a00
	s_addc_u32 s23, s7, 0
	s_add_u32 s24, s6, 0x4b00
	s_addc_u32 s25, s7, 0
	s_add_u32 s26, s6, 0x4c00
	s_addc_u32 s27, s7, 0
	s_add_u32 s28, s6, 0x4d00
	s_addc_u32 s29, s7, 0
	s_add_u32 s30, s6, 0x4e00
	s_addc_u32 s31, s7, 0
	s_add_u32 s34, s6, 0x4f00
	s_addc_u32 s35, s7, 0
	s_add_u32 s36, s6, 0x5000
	s_addc_u32 s37, s7, 0
	s_add_u32 s38, s6, 0x5100
	s_addc_u32 s39, s7, 0
	s_add_u32 s40, s6, 0x5200
	s_addc_u32 s41, s7, 0
	s_add_u32 s42, s6, 0x5300
	s_mul_i32 s58, s58, s52
	s_addc_u32 s43, s7, 0
	s_branch .LBB0_237

.LBB0_518:
	s_mov_b64 s[6:7], s[0:1]
	s_getreg_b32 s8, hwreg(HW_REG_XCC_ID, 0, 4)
	s_waitcnt vmcnt(0)
	s_barrier
	s_and_saveexec_b64 s[4:5], s[44:45]
	s_cbranch_execz .LBB0_570
	s_cmp_eq_u32 s99, 0
	s_cbranch_scc1 .Lfb_skip_1
	s_load_dwordx2 s[8:9], s[0:1], 0x80
	s_and_b32 s10, s2, 7
	s_lshl_b32 s10, s10, 8
	s_add_i32 s10, s10, 0x1000
	s_lshr_b32 s11, s2, 3
	v_mov_b32_e32 v0, 2
	v_mov_b32_e32 v3, 0
	s_lshl_b32 s12, s11, 2
	v_mov_b32_e32 v1, s12
	s_mov_b32 s13, 0
	s_waitcnt lgkmcnt(0)
	s_add_u32 s8, s8, s10
	s_addc_u32 s9, s9, 0
	global_store_dword v1, v0, s[8:9]
	buffer_inv sc1
	s_cmp_eq_u32 s11, 0
	s_cbranch_scc1 .Lfb_lead_1

.Lfb_lead_1:
	s_mov_b64 s[16:17], exec
	s_mov_b64 exec, 0xffffffff
	v_mbcnt_lo_u32_b32 v4, -1, 0
	v_lshlrev_b32_e32 v4, 2, v4
	v_mov_b32_e32 v0, 2

.Lfb_skip_1:
	s_add_i32 s9, 0, 0x23fe0
	v_mov_b32_e32 v0, s9
	s_load_dwordx2 s[6:7], s[6:7], 0x80
	s_waitcnt vmcnt(0) expcnt(0) lgkmcnt(0)
	ds_read_b32 v2, v0
	s_add_i32 s9, 0, 0x23fe4
	v_mov_b32_e32 v0, s9
	ds_read_b32 v0, v0
	s_and_b32 s33, s8, 15
	s_waitcnt lgkmcnt(1)
	v_cmp_ne_u32_e32 vcc, 0, v2
	s_cbranch_vccnz .LBB0_534
	s_load_dword s8, s[0:1], 0x90
	s_mov_b32 s55, 1
	v_mov_b32_e32 v16, 0
	s_waitcnt lgkmcnt(0)
	s_mul_i32 s54, s53, s8
	s_add_u32 s8, s6, 0x4200
	s_addc_u32 s9, s7, 0
	s_add_u32 s10, s6, 0x4400
	s_addc_u32 s11, s7, 0
	s_add_u32 s12, s6, 0x4500
	s_addc_u32 s13, s7, 0
	s_add_u32 s16, s6, 0x4600
	s_addc_u32 s17, s7, 0
	s_add_u32 s18, s6, 0x4700
	s_addc_u32 s19, s7, 0
	s_add_u32 s20, s6, 0x4800
	s_addc_u32 s21, s7, 0
	s_add_u32 s22, s6, 0x4900
	s_addc_u32 s23, s7, 0
	s_add_u32 s24, s6, 0x4a00
	s_addc_u32 s25, s7, 0
	s_add_u32 s26, s6, 0x4b00
	s_addc_u32 s27, s7, 0
	s_add_u32 s28, s6, 0x4c00
	s_addc_u32 s29, s7, 0
	s_add_u32 s30, s6, 0x4d00
	s_addc_u32 s31, s7, 0
	s_add_u32 s34, s6, 0x4e00
	s_addc_u32 s35, s7, 0
	s_add_u32 s36, s6, 0x4f00
	s_addc_u32 s37, s7, 0
	s_add_u32 s38, s6, 0x5000
	s_addc_u32 s39, s7, 0
	s_add_u32 s40, s6, 0x5100
	s_addc_u32 s41, s7, 0
	s_add_u32 s42, s6, 0x5200
	s_addc_u32 s43, s7, 0
	s_add_u32 s48, s6, 0x5300
	s_mul_i32 s54, s54, s52
	s_addc_u32 s49, s7, 0
	s_branch .LBB0_522

.LBB0_612:
	s_mov_b64 s[8:9], s[0:1]
	s_waitcnt lgkmcnt(0)
	s_getreg_b32 s10, hwreg(HW_REG_XCC_ID, 0, 4)
	s_waitcnt vmcnt(0)
	s_barrier
	s_and_saveexec_b64 s[6:7], s[44:45]
	s_cbranch_execz .LBB0_664
	s_cmp_eq_u32 s99, 0
	s_cbranch_scc1 .Lfb_skip_2
	s_load_dwordx2 s[8:9], s[0:1], 0x80
	s_and_b32 s10, s2, 7
	s_lshl_b32 s10, s10, 8
	s_add_i32 s10, s10, 0x1000
	s_lshr_b32 s11, s2, 3
	v_mov_b32_e32 v0, 3
	v_mov_b32_e32 v3, 0
	s_lshl_b32 s12, s11, 2
	v_mov_b32_e32 v1, s12
	s_mov_b32 s13, 0
	s_waitcnt lgkmcnt(0)
	s_add_u32 s8, s8, s10
	s_addc_u32 s9, s9, 0
	global_store_dword v1, v0, s[8:9]
	buffer_inv sc1
	s_cmp_eq_u32 s11, 0
	s_cbranch_scc1 .Lfb_lead_2

.Lfb_lead_2:
	s_mov_b64 s[16:17], exec
	s_mov_b64 exec, 0xffffffff
	v_mbcnt_lo_u32_b32 v4, -1, 0
	v_lshlrev_b32_e32 v4, 2, v4
	v_mov_b32_e32 v0, 3

.Lfb_skip_2:
	s_add_i32 s11, 0, 0x23fe0
	v_mov_b32_e32 v0, s11
	s_load_dwordx2 s[8:9], s[8:9], 0x80
	s_waitcnt vmcnt(0) expcnt(0) lgkmcnt(0)
	ds_read_b32 v2, v0
	s_add_i32 s11, 0, 0x23fe4
	v_mov_b32_e32 v0, s11
	ds_read_b32 v0, v0
	s_and_b32 s33, s10, 15
	s_waitcnt lgkmcnt(1)
	v_cmp_ne_u32_e32 vcc, 0, v2
	s_cbranch_vccnz .LBB0_628
	s_load_dword s10, s[0:1], 0x90
	s_mov_b32 s55, 1
	v_mov_b32_e32 v16, 0
	s_waitcnt lgkmcnt(0)
	s_mul_i32 s54, s53, s10
	s_add_u32 s10, s8, 0x4200
	s_addc_u32 s11, s9, 0
	s_add_u32 s12, s8, 0x4400
	s_addc_u32 s13, s9, 0
	s_add_u32 s14, s8, 0x4500
	s_addc_u32 s15, s9, 0
	s_add_u32 s16, s8, 0x4600
	s_addc_u32 s17, s9, 0
	s_add_u32 s18, s8, 0x4700
	s_addc_u32 s19, s9, 0
	s_add_u32 s20, s8, 0x4800
	s_addc_u32 s21, s9, 0
	s_add_u32 s22, s8, 0x4900
	s_addc_u32 s23, s9, 0
	s_add_u32 s24, s8, 0x4a00
	s_addc_u32 s25, s9, 0
	s_add_u32 s26, s8, 0x4b00
	s_addc_u32 s27, s9, 0
	s_add_u32 s28, s8, 0x4c00
	s_addc_u32 s29, s9, 0
	s_add_u32 s30, s8, 0x4d00
	s_addc_u32 s31, s9, 0
	s_add_u32 s34, s8, 0x4e00
	s_addc_u32 s35, s9, 0
	s_add_u32 s36, s8, 0x4f00
	s_addc_u32 s37, s9, 0
	s_add_u32 s38, s8, 0x5000
	s_addc_u32 s39, s9, 0
	s_add_u32 s40, s8, 0x5100
	s_addc_u32 s41, s9, 0
	s_add_u32 s42, s8, 0x5200
	s_addc_u32 s43, s9, 0
	s_add_u32 s48, s8, 0x5300
	s_mul_i32 s54, s54, s52
	s_addc_u32 s49, s9, 0
	s_branch .LBB0_616

.LBB0_1112:
	s_mov_b64 s[8:9], s[0:1]
	s_getreg_b32 s10, hwreg(HW_REG_XCC_ID, 0, 4)
	s_waitcnt vmcnt(0)
	s_barrier
	s_and_saveexec_b64 s[6:7], s[44:45]
	s_cbranch_execz .LBB0_1164
	s_cmp_eq_u32 s99, 0
	s_cbranch_scc1 .Lfb_skip_3
	s_load_dwordx2 s[8:9], s[0:1], 0x80
	s_and_b32 s10, s2, 7
	s_lshl_b32 s10, s10, 8
	s_add_i32 s10, s10, 0x1000
	s_lshr_b32 s11, s2, 3
	v_mov_b32_e32 v0, 4
	v_mov_b32_e32 v3, 0
	s_lshl_b32 s12, s11, 2
	v_mov_b32_e32 v1, s12
	s_mov_b32 s13, 0
	s_waitcnt lgkmcnt(0)
	s_add_u32 s8, s8, s10
	s_addc_u32 s9, s9, 0
	global_store_dword v1, v0, s[8:9]
	buffer_inv sc1
	s_cmp_eq_u32 s11, 0
	s_cbranch_scc1 .Lfb_lead_3

.Lfb_lead_3:
	s_mov_b64 s[16:17], exec
	s_mov_b64 exec, 0xffffffff
	v_mbcnt_lo_u32_b32 v4, -1, 0
	v_lshlrev_b32_e32 v4, 2, v4
	v_mov_b32_e32 v0, 4

.Lfb_skip_3:
	s_add_i32 s11, 0, 0x23fe0
	s_waitcnt vmcnt(17)
	v_mov_b32_e32 v0, s11
	s_load_dwordx2 s[8:9], s[8:9], 0x80
	s_waitcnt vmcnt(0) expcnt(0) lgkmcnt(0)
	ds_read_b32 v2, v0
	s_add_i32 s11, 0, 0x23fe4
	v_mov_b32_e32 v0, s11
	ds_read_b32 v0, v0
	s_and_b32 s33, s10, 15
	s_waitcnt lgkmcnt(1)
	v_cmp_ne_u32_e32 vcc, 0, v2
	s_cbranch_vccnz .LBB0_1128
	s_load_dword s10, s[0:1], 0x90
	s_mov_b32 s55, 1
	v_mov_b32_e32 v16, 0
	s_waitcnt lgkmcnt(0)
	s_mul_i32 s54, s53, s10
	s_add_u32 s10, s8, 0x4200
	s_addc_u32 s11, s9, 0
	s_add_u32 s12, s8, 0x4400
	s_addc_u32 s13, s9, 0
	s_add_u32 s16, s8, 0x4500
	s_addc_u32 s17, s9, 0
	s_add_u32 s18, s8, 0x4600
	s_addc_u32 s19, s9, 0
	s_add_u32 s20, s8, 0x4700
	s_addc_u32 s21, s9, 0
	s_add_u32 s22, s8, 0x4800
	s_addc_u32 s23, s9, 0
	s_add_u32 s24, s8, 0x4900
	s_addc_u32 s25, s9, 0
	s_add_u32 s26, s8, 0x4a00
	s_addc_u32 s27, s9, 0
	s_add_u32 s28, s8, 0x4b00
	s_addc_u32 s29, s9, 0
	s_add_u32 s30, s8, 0x4c00
	s_addc_u32 s31, s9, 0
	s_add_u32 s34, s8, 0x4d00
	s_addc_u32 s35, s9, 0
	s_add_u32 s36, s8, 0x4e00
	s_addc_u32 s37, s9, 0
	s_add_u32 s38, s8, 0x4f00
	s_addc_u32 s39, s9, 0
	s_add_u32 s40, s8, 0x5000
	s_addc_u32 s41, s9, 0
	s_add_u32 s42, s8, 0x5100
	s_addc_u32 s43, s9, 0
	s_add_u32 s48, s8, 0x5200
	s_addc_u32 s49, s9, 0
	s_add_u32 s50, s8, 0x5300
	s_mul_i32 s54, s54, s52
	s_addc_u32 s51, s9, 0
	s_branch .LBB0_1116

.LBB0_1210:
	s_mov_b64 s[8:9], s[0:1]
	s_getreg_b32 s10, hwreg(HW_REG_XCC_ID, 0, 4)
	s_waitcnt vmcnt(0)
	s_waitcnt lgkmcnt(0)
	s_barrier
	s_and_saveexec_b64 s[6:7], s[44:45]
	s_cbranch_execz .LBB0_1262
	s_cmp_eq_u32 s99, 0
	s_cbranch_scc1 .Lfb_skip_4
	s_load_dwordx2 s[8:9], s[0:1], 0x80
	s_and_b32 s10, s2, 7
	s_lshl_b32 s10, s10, 8
	s_add_i32 s10, s10, 0x1000
	s_lshr_b32 s11, s2, 3
	v_mov_b32_e32 v0, 5
	v_mov_b32_e32 v3, 0
	s_lshl_b32 s12, s11, 2
	v_mov_b32_e32 v1, s12
	s_mov_b32 s13, 0
	s_waitcnt lgkmcnt(0)
	s_add_u32 s8, s8, s10
	s_addc_u32 s9, s9, 0
	global_store_dword v1, v0, s[8:9]
	buffer_inv sc1
	s_cmp_eq_u32 s11, 0
	s_cbranch_scc1 .Lfb_lead_4

.Lfb_lead_4:
	s_mov_b64 s[16:17], exec
	s_mov_b64 exec, 0xffffffff
	v_mbcnt_lo_u32_b32 v4, -1, 0
	v_lshlrev_b32_e32 v4, 2, v4
	v_mov_b32_e32 v0, 5

.Lfb_skip_4:
	s_add_i32 s11, 0, 0x23fe0
	v_mov_b32_e32 v0, s11
	s_load_dwordx2 s[8:9], s[8:9], 0x80
	s_waitcnt vmcnt(0) expcnt(0) lgkmcnt(0)
	ds_read_b32 v2, v0
	s_add_i32 s11, 0, 0x23fe4
	v_mov_b32_e32 v0, s11
	ds_read_b32 v0, v0
	s_and_b32 s33, s10, 15
	s_waitcnt lgkmcnt(1)
	v_cmp_ne_u32_e32 vcc, 0, v2
	s_cbranch_vccnz .LBB0_1226
	s_load_dword s10, s[0:1], 0x90
	s_mov_b32 s55, 1
	v_mov_b32_e32 v16, 0
	s_waitcnt lgkmcnt(0)
	s_mul_i32 s54, s53, s10
	s_add_u32 s10, s8, 0x4200
	s_addc_u32 s11, s9, 0
	s_add_u32 s12, s8, 0x4400
	s_addc_u32 s13, s9, 0
	s_add_u32 s16, s8, 0x4500
	s_addc_u32 s17, s9, 0
	s_add_u32 s18, s8, 0x4600
	s_addc_u32 s19, s9, 0
	s_add_u32 s20, s8, 0x4700
	s_addc_u32 s21, s9, 0
	s_add_u32 s22, s8, 0x4800
	s_addc_u32 s23, s9, 0
	s_add_u32 s24, s8, 0x4900
	s_addc_u32 s25, s9, 0
	s_add_u32 s26, s8, 0x4a00
	s_addc_u32 s27, s9, 0
	s_add_u32 s28, s8, 0x4b00
	s_addc_u32 s29, s9, 0
	s_add_u32 s30, s8, 0x4c00
	s_addc_u32 s31, s9, 0
	s_add_u32 s34, s8, 0x4d00
	s_addc_u32 s35, s9, 0
	s_add_u32 s36, s8, 0x4e00
	s_addc_u32 s37, s9, 0
	s_add_u32 s38, s8, 0x4f00
	s_addc_u32 s39, s9, 0
	s_add_u32 s40, s8, 0x5000
	s_addc_u32 s41, s9, 0
	s_add_u32 s42, s8, 0x5100
	s_addc_u32 s43, s9, 0
	s_add_u32 s48, s8, 0x5200
	s_addc_u32 s49, s9, 0
	s_add_u32 s50, s8, 0x5300
	s_mul_i32 s54, s54, s52
	s_addc_u32 s51, s9, 0
	s_branch .LBB0_1214

.LBB0_1349:
	s_mov_b64 s[8:9], s[0:1]
	s_getreg_b32 s10, hwreg(HW_REG_XCC_ID, 0, 4)
	s_waitcnt vmcnt(0)
	s_barrier
	s_and_saveexec_b64 s[6:7], s[44:45]
	s_cbranch_execz .LBB0_1401
	s_cmp_eq_u32 s99, 0
	s_cbranch_scc1 .Lfb_skip_5
	s_load_dwordx2 s[8:9], s[0:1], 0x80
	s_and_b32 s10, s2, 7
	s_lshl_b32 s10, s10, 8
	s_add_i32 s10, s10, 0x1000
	s_lshr_b32 s11, s2, 3
	v_mov_b32_e32 v0, 6
	v_mov_b32_e32 v3, 0
	s_lshl_b32 s12, s11, 2
	v_mov_b32_e32 v1, s12
	s_mov_b32 s13, 0
	s_waitcnt lgkmcnt(0)
	s_add_u32 s8, s8, s10
	s_addc_u32 s9, s9, 0
	global_store_dword v1, v0, s[8:9]
	buffer_inv sc1
	s_cmp_eq_u32 s11, 0
	s_cbranch_scc1 .Lfb_lead_5

.Lfb_lead_5:
	s_mov_b64 s[16:17], exec
	s_mov_b64 exec, 0xffffffff
	v_mbcnt_lo_u32_b32 v4, -1, 0
	v_lshlrev_b32_e32 v4, 2, v4
	v_mov_b32_e32 v0, 6

.LBB0_1443:
	s_mov_b64 s[8:9], s[0:1]
	s_getreg_b32 s10, hwreg(HW_REG_XCC_ID, 0, 4)
	s_waitcnt vmcnt(0)
	s_waitcnt lgkmcnt(0)
	s_barrier
	s_and_saveexec_b64 s[6:7], s[44:45]
	s_cbranch_execz .LBB0_1495
	s_cmp_eq_u32 s99, 0
	s_cbranch_scc1 .Lfb_skip_6
	s_load_dwordx2 s[8:9], s[0:1], 0x80
	s_and_b32 s10, s2, 7
	s_lshl_b32 s10, s10, 8
	s_add_i32 s10, s10, 0x1000
	s_lshr_b32 s11, s2, 3
	v_mov_b32_e32 v0, 7
	v_mov_b32_e32 v3, 0
	s_lshl_b32 s12, s11, 2
	v_mov_b32_e32 v1, s12
	s_mov_b32 s13, 0
	s_waitcnt lgkmcnt(0)
	s_add_u32 s8, s8, s10
	s_addc_u32 s9, s9, 0
	global_store_dword v1, v0, s[8:9]
	buffer_inv sc1
	s_cmp_eq_u32 s11, 0
	s_cbranch_scc1 .Lfb_lead_6

.Lfb_lead_6:
	s_mov_b64 s[16:17], exec
	s_mov_b64 exec, 0xffffffff
	v_mbcnt_lo_u32_b32 v4, -1, 0
	v_lshlrev_b32_e32 v4, 2, v4
	v_mov_b32_e32 v0, 7
